# FFN-in SwiGLU epilogue: 8 of the 4-element blocks re-emitted with packed f32 ops (v_pk_mul/v_pk_add, same per-element operations)
# baseline (speedup 1.0000x reference)
.LBB0_673:
	v_add3_u32 v132, v136, v137, s52
	ds_read_b128 v[128:131], v132
	ds_read_b128 v[138:141], v132 offset:2048
	ds_read_b128 v[154:157], v132 offset:4096
	ds_read_b128 v[158:161], v132 offset:6144
	v_add3_u32 v132, v134, v137, s81
	ds_read_b128 v[162:165], v132
	ds_read_b128 v[166:169], v132 offset:2048
	ds_read_b128 v[170:173], v132 offset:4096
	ds_read_b128 v[174:177], v132 offset:6144
	ds_read_b128 v[178:181], v132 offset:8192
	ds_read_b128 v[182:185], v132 offset:10240
	ds_read_b128 v[186:189], v132 offset:12288
	ds_read_b128 v[216:219], v132 offset:14336
	s_waitcnt lgkmcnt(0)
	v_mfma_f32_16x16x32_bf16 v[116:119], v[128:131], v[162:165], v[116:119]
	v_mfma_f32_16x16x32_bf16 v[108:111], v[138:141], v[162:165], v[108:111]
	v_mfma_f32_16x16x32_bf16 v[100:103], v[154:157], v[162:165], v[100:103]
	v_mfma_f32_16x16x32_bf16 v[88:91], v[158:161], v[162:165], v[88:91]
	v_mfma_f32_16x16x32_bf16 v[76:79], v[128:131], v[166:169], v[76:79]
	v_mfma_f32_16x16x32_bf16 v[68:71], v[138:141], v[166:169], v[68:71]
	v_mfma_f32_16x16x32_bf16 v[56:59], v[154:157], v[166:169], v[56:59]
	v_mfma_f32_16x16x32_bf16 v[44:47], v[158:161], v[166:169], v[44:47]
	v_mfma_f32_16x16x32_bf16 v[36:39], v[128:131], v[170:173], v[36:39]
	v_mfma_f32_16x16x32_bf16 v[32:35], v[138:141], v[170:173], v[32:35]
	v_mfma_f32_16x16x32_bf16 v[28:31], v[154:157], v[170:173], v[28:31]
	v_mfma_f32_16x16x32_bf16 v[24:27], v[158:161], v[170:173], v[24:27]
	v_mfma_f32_16x16x32_bf16 v[20:23], v[128:131], v[174:177], v[20:23]
	v_mfma_f32_16x16x32_bf16 v[16:19], v[138:141], v[174:177], v[16:19]
	v_mfma_f32_16x16x32_bf16 v[12:15], v[154:157], v[174:177], v[12:15]
	v_mfma_f32_16x16x32_bf16 v[8:11], v[158:161], v[174:177], v[8:11]
	v_add3_u32 v132, v136, v135, s52
	v_add3_u32 v144, v134, v135, s81
	ds_read_b128 v[162:165], v132
	ds_read_b128 v[166:169], v132 offset:2048
	ds_read_b128 v[170:173], v132 offset:4096
	ds_read_b128 v[174:177], v132 offset:6144
	ds_read_b128 v[132:135], v144
	ds_read_b128 v[220:223], v144 offset:2048
	ds_read_b128 v[224:227], v144 offset:4096
	ds_read_b128 v[228:231], v144 offset:6144
	v_mfma_f32_16x16x32_bf16 v[4:7], v[128:131], v[178:181], v[4:7]
	v_mfma_f32_16x16x32_bf16 v[0:3], v[138:141], v[178:181], v[0:3]
	v_mfma_f32_16x16x32_bf16 v[40:43], v[154:157], v[178:181], v[40:43]
	v_mfma_f32_16x16x32_bf16 v[48:51], v[158:161], v[178:181], v[48:51]
	v_mfma_f32_16x16x32_bf16 v[178:181], v[128:131], v[182:185], v[52:55]
	v_mfma_f32_16x16x32_bf16 v[232:235], v[138:141], v[182:185], v[60:63]
	v_mfma_f32_16x16x32_bf16 v[236:239], v[154:157], v[182:185], v[64:67]
	v_mfma_f32_16x16x32_bf16 v[182:185], v[158:161], v[182:185], v[72:75]
	v_mfma_f32_16x16x32_bf16 v[240:243], v[128:131], v[186:189], v[80:83]
	v_mfma_f32_16x16x32_bf16 v[244:247], v[138:141], v[186:189], v[84:87]
	v_mfma_f32_16x16x32_bf16 v[248:251], v[154:157], v[186:189], v[92:95]
	v_mfma_f32_16x16x32_bf16 v[186:189], v[158:161], v[186:189], v[96:99]
	v_mfma_f32_16x16x32_bf16 v[128:131], v[128:131], v[216:219], v[104:107]
	v_mfma_f32_16x16x32_bf16 v[136:139], v[138:141], v[216:219], v[112:115]
	v_mfma_f32_16x16x32_bf16 v[140:143], v[154:157], v[216:219], v[120:123]
	v_mfma_f32_16x16x32_bf16 v[154:157], v[158:161], v[216:219], v[124:127]
	ds_read_b128 v[158:161], v144 offset:8192
	ds_read_b128 v[216:219], v144 offset:10240
	ds_read_b128 v[146:149], v144 offset:12288
	ds_read_b128 v[206:209], v144 offset:14336
	s_waitcnt lgkmcnt(0)
	v_mfma_f32_16x16x32_bf16 v[124:127], v[162:165], v[132:135], v[116:119]
	v_mfma_f32_16x16x32_bf16 v[120:123], v[166:169], v[132:135], v[108:111]
	v_mfma_f32_16x16x32_bf16 v[116:119], v[170:173], v[132:135], v[100:103]
	v_mfma_f32_16x16x32_bf16 v[112:115], v[174:177], v[132:135], v[88:91]
	v_mfma_f32_16x16x32_bf16 v[108:111], v[162:165], v[220:223], v[76:79]
	v_mfma_f32_16x16x32_bf16 v[104:107], v[166:169], v[220:223], v[68:71]
	v_mfma_f32_16x16x32_bf16 v[100:103], v[170:173], v[220:223], v[56:59]
	v_mfma_f32_16x16x32_bf16 v[96:99], v[174:177], v[220:223], v[44:47]
	v_mfma_f32_16x16x32_bf16 v[92:95], v[162:165], v[224:227], v[36:39]
	v_mfma_f32_16x16x32_bf16 v[88:91], v[166:169], v[224:227], v[32:35]
	v_mfma_f32_16x16x32_bf16 v[84:87], v[170:173], v[224:227], v[28:31]
	v_mfma_f32_16x16x32_bf16 v[80:83], v[174:177], v[224:227], v[24:27]
	v_mfma_f32_16x16x32_bf16 v[76:79], v[162:165], v[228:231], v[20:23]
	v_mfma_f32_16x16x32_bf16 v[72:75], v[166:169], v[228:231], v[16:19]
	v_mfma_f32_16x16x32_bf16 v[68:71], v[170:173], v[228:231], v[12:15]
	v_mfma_f32_16x16x32_bf16 v[64:67], v[174:177], v[228:231], v[8:11]
	v_mfma_f32_16x16x32_bf16 v[60:63], v[162:165], v[158:161], v[4:7]
	s_lshl_b32 s0, s26, 8
	s_mov_b64 s[2:3], -1
	s_and_b64 vcc, exec, s[24:25]
	v_mfma_f32_16x16x32_bf16 v[56:59], v[166:169], v[158:161], v[0:3]
	v_mfma_f32_16x16x32_bf16 v[52:55], v[170:173], v[158:161], v[40:43]
	v_mfma_f32_16x16x32_bf16 v[48:51], v[174:177], v[158:161], v[48:51]
	v_mfma_f32_16x16x32_bf16 v[44:47], v[162:165], v[216:219], v[178:181]
	v_mfma_f32_16x16x32_bf16 v[40:43], v[166:169], v[216:219], v[232:235]
	v_mfma_f32_16x16x32_bf16 v[36:39], v[170:173], v[216:219], v[236:239]
	v_mfma_f32_16x16x32_bf16 v[32:35], v[174:177], v[216:219], v[182:185]
	v_mfma_f32_16x16x32_bf16 v[28:31], v[162:165], v[146:149], v[240:243]
	v_mfma_f32_16x16x32_bf16 v[24:27], v[166:169], v[146:149], v[244:247]
	v_mfma_f32_16x16x32_bf16 v[20:23], v[170:173], v[146:149], v[248:251]
	v_mfma_f32_16x16x32_bf16 v[16:19], v[174:177], v[146:149], v[186:189]
	v_mfma_f32_16x16x32_bf16 v[12:15], v[162:165], v[206:209], v[128:131]
	v_mfma_f32_16x16x32_bf16 v[8:11], v[166:169], v[206:209], v[136:139]
	v_mfma_f32_16x16x32_bf16 v[4:7], v[170:173], v[206:209], v[140:143]
	v_mfma_f32_16x16x32_bf16 v[0:3], v[174:177], v[206:209], v[154:157]
	s_cbranch_vccz .LBB0_675
	s_mov_b32 s98, 0xbfb8aa3b
	v_mov_b32_e32 v128, v190
	s_lshl_b32 s2, s22, 7
	v_ashrrev_i32_e32 v130, 1, v128
	v_and_b32_e32 v129, 15, v128
	v_and_b32_e32 v130, 0xffffff80, v130
	v_or_b32_e32 v131, s0, v129
	v_or_b32_e32 v129, v130, v129
	v_add_u32_e32 v131, v131, v130
	v_lshl_add_u32 v130, v129, 2, v205
	ds_read_b32 v136, v130
	s_ashr_i32 s3, s2, 31
	s_lshl_b64 s[2:3], s[2:3], 1
	s_add_u32 s2, s66, s2
	s_addc_u32 s3, s67, s3
	s_waitcnt lgkmcnt(0)
	v_lshrrev_b32_e32 v132, 1, v128
	v_and_b32_e32 v144, 0xc0, v128
	v_lshl_add_u64 v[128:129], s[2:3], 0, v[144:145]
	v_and_b32_e32 v144, 24, v132
	v_lshl_add_u64 v[128:129], v[128:129], 0, v[144:145]
	v_and_b32_e32 v144, 8, v144
	v_mul_u32_u24_e32 v144, 3, v144
	v_lshl_add_u64 v[128:129], v[128:129], 0, v[144:145]
	v_mad_i64_i32 v[132:133], s[2:3], v131, s33, v[128:129]
	s_nop 0
	v_pk_mul_f32 v[216:217], v[124:125], v[136:137] op_sel_hi:[1,0]
	v_pk_mul_f32 v[218:219], v[126:127], v[136:137] op_sel_hi:[1,0]
	v_pk_mul_f32 v[220:221], v[216:217], s[98:99] op_sel_hi:[1,0]
	v_pk_mul_f32 v[222:223], v[218:219], s[98:99] op_sel_hi:[1,0]
	v_exp_f32_e32 v220, v220
	v_exp_f32_e32 v221, v221
	v_exp_f32_e32 v222, v222
	v_exp_f32_e32 v223, v223
	v_pk_add_f32 v[220:221], v[220:221], 1.0 op_sel_hi:[1,0]
	v_pk_add_f32 v[222:223], v[222:223], 1.0 op_sel_hi:[1,0]
	v_rcp_f32_e32 v220, v220
	v_rcp_f32_e32 v221, v221
	v_rcp_f32_e32 v222, v222
	v_rcp_f32_e32 v223, v223
	v_pk_mul_f32 v[216:217], v[216:217], v[220:221]
	v_pk_mul_f32 v[218:219], v[218:219], v[222:223]
	v_pk_mul_f32 v[220:221], v[120:121], v[136:137] op_sel_hi:[1,0]
	v_pk_mul_f32 v[222:223], v[122:123], v[136:137] op_sel_hi:[1,0]
	v_pk_mul_f32 v[216:217], v[220:221], v[216:217]
	v_pk_mul_f32 v[218:219], v[222:223], v[218:219]
	v_cvt_pk_bf16_f32 v134, v216, v217
	v_cvt_pk_bf16_f32 v135, v218, v219
	s_waitcnt vmcnt(0)
	v_mov_b32_e32 v248, v134
	v_mov_b32_e32 v249, v135
	v_mul_f32_e32 v134, v116, v136
	v_mul_f32_e32 v135, 0xbfb8aa3b, v134
	v_exp_f32_e32 v135, v135
	s_nop 0
	v_add_f32_e32 v135, 1.0, v135
	v_rcp_f32_e32 v135, v135
	s_nop 0
	v_mul_f32_e32 v134, v134, v135
	v_mul_f32_e32 v135, v112, v136
	v_mul_f32_e32 v134, v135, v134
	v_mul_f32_e32 v135, v117, v136
	v_mul_f32_e32 v137, 0xbfb8aa3b, v135
	v_exp_f32_e32 v137, v137
	s_nop 0
	v_add_f32_e32 v137, 1.0, v137
	v_rcp_f32_e32 v137, v137
	s_nop 0
	v_mul_f32_e32 v135, v135, v137
	v_mul_f32_e32 v137, v113, v136
	v_mul_f32_e32 v135, v137, v135
	v_mul_f32_e32 v137, v118, v136
	v_mul_f32_e32 v138, 0xbfb8aa3b, v137
	v_exp_f32_e32 v138, v138
	v_cvt_pk_bf16_f32 v134, v134, v135
	s_nop 0
	v_add_f32_e32 v138, 1.0, v138
	v_rcp_f32_e32 v138, v138
	s_nop 0
	v_mul_f32_e32 v137, v137, v138
	v_mul_f32_e32 v138, v114, v136
	v_mul_f32_e32 v137, v138, v137
	v_mul_f32_e32 v138, v119, v136
	v_mul_f32_e32 v139, 0xbfb8aa3b, v138
	v_exp_f32_e32 v139, v139
	v_mul_f32_e32 v136, v115, v136
	v_add_f32_e32 v139, 1.0, v139
	v_rcp_f32_e32 v139, v139
	s_nop 0
	v_mul_f32_e32 v138, v138, v139
	v_mul_f32_e32 v136, v136, v138
	v_cvt_pk_bf16_f32 v135, v137, v136
	v_mov_b32_e32 v250, v134
	v_mov_b32_e32 v251, v135
	s_nop 1
	v_permlane16_swap_b32 v248, v250
	v_permlane16_swap_b32 v249, v251
	flat_store_dwordx4 v[132:133], v[248:251]
	ds_read_b32 v136, v130 offset:64
	v_or_b32_e32 v132, 16, v131
	v_mad_i64_i32 v[132:133], s[2:3], v132, s33, v[128:129]
	s_waitcnt lgkmcnt(0)
	s_nop 0
	v_pk_mul_f32 v[216:217], v[108:109], v[136:137] op_sel_hi:[1,0]
	v_pk_mul_f32 v[218:219], v[110:111], v[136:137] op_sel_hi:[1,0]
	v_pk_mul_f32 v[220:221], v[216:217], s[98:99] op_sel_hi:[1,0]
	v_pk_mul_f32 v[222:223], v[218:219], s[98:99] op_sel_hi:[1,0]
	v_exp_f32_e32 v220, v220
	v_exp_f32_e32 v221, v221
	v_exp_f32_e32 v222, v222
	v_exp_f32_e32 v223, v223
	v_pk_add_f32 v[220:221], v[220:221], 1.0 op_sel_hi:[1,0]
	v_pk_add_f32 v[222:223], v[222:223], 1.0 op_sel_hi:[1,0]
	v_rcp_f32_e32 v220, v220
	v_rcp_f32_e32 v221, v221
	v_rcp_f32_e32 v222, v222
	v_rcp_f32_e32 v223, v223
	v_pk_mul_f32 v[216:217], v[216:217], v[220:221]
	v_pk_mul_f32 v[218:219], v[218:219], v[222:223]
	v_pk_mul_f32 v[220:221], v[104:105], v[136:137] op_sel_hi:[1,0]
	v_pk_mul_f32 v[222:223], v[106:107], v[136:137] op_sel_hi:[1,0]
	v_pk_mul_f32 v[216:217], v[220:221], v[216:217]
	v_pk_mul_f32 v[218:219], v[222:223], v[218:219]
	v_cvt_pk_bf16_f32 v134, v216, v217
	v_cvt_pk_bf16_f32 v135, v218, v219
	v_mov_b32_e32 v248, v134
	v_mov_b32_e32 v249, v135
	v_mul_f32_e32 v134, v100, v136
	v_mul_f32_e32 v135, 0xbfb8aa3b, v134
	v_exp_f32_e32 v135, v135
	s_nop 0
	v_add_f32_e32 v135, 1.0, v135
	v_rcp_f32_e32 v135, v135
	s_nop 0
	v_mul_f32_e32 v134, v134, v135
	v_mul_f32_e32 v135, v96, v136
	v_mul_f32_e32 v134, v135, v134
	v_mul_f32_e32 v135, v101, v136
	v_mul_f32_e32 v137, 0xbfb8aa3b, v135
	v_exp_f32_e32 v137, v137
	s_nop 0
	v_add_f32_e32 v137, 1.0, v137
	v_rcp_f32_e32 v137, v137
	s_nop 0
	v_mul_f32_e32 v135, v135, v137
	v_mul_f32_e32 v137, v97, v136
	v_mul_f32_e32 v135, v137, v135
	v_mul_f32_e32 v137, v102, v136
	v_mul_f32_e32 v138, 0xbfb8aa3b, v137
	v_exp_f32_e32 v138, v138
	v_cvt_pk_bf16_f32 v134, v134, v135
	s_nop 0
	v_add_f32_e32 v138, 1.0, v138
	v_rcp_f32_e32 v138, v138
	s_nop 0
	v_mul_f32_e32 v137, v137, v138
	v_mul_f32_e32 v138, v98, v136
	v_mul_f32_e32 v137, v138, v137
	v_mul_f32_e32 v138, v103, v136
	v_mul_f32_e32 v139, 0xbfb8aa3b, v138
	v_exp_f32_e32 v139, v139
	v_mul_f32_e32 v136, v99, v136
	v_add_f32_e32 v139, 1.0, v139
	v_rcp_f32_e32 v139, v139
	s_nop 0
	v_mul_f32_e32 v138, v138, v139
	v_mul_f32_e32 v136, v136, v138
	v_cvt_pk_bf16_f32 v135, v137, v136
	v_mov_b32_e32 v250, v134
	v_mov_b32_e32 v251, v135
	s_nop 1
	v_permlane16_swap_b32 v248, v250
	v_permlane16_swap_b32 v249, v251
	flat_store_dwordx4 v[132:133], v[248:251]
	ds_read_b32 v136, v130 offset:128
	v_or_b32_e32 v132, 32, v131
	v_mad_i64_i32 v[132:133], s[2:3], v132, s33, v[128:129]
	s_waitcnt lgkmcnt(0)
	s_nop 0
	v_pk_mul_f32 v[216:217], v[92:93], v[136:137] op_sel_hi:[1,0]
	v_pk_mul_f32 v[218:219], v[94:95], v[136:137] op_sel_hi:[1,0]
	v_pk_mul_f32 v[220:221], v[216:217], s[98:99] op_sel_hi:[1,0]
	v_pk_mul_f32 v[222:223], v[218:219], s[98:99] op_sel_hi:[1,0]
	v_exp_f32_e32 v220, v220
	v_exp_f32_e32 v221, v221
	v_exp_f32_e32 v222, v222
	v_exp_f32_e32 v223, v223
	v_pk_add_f32 v[220:221], v[220:221], 1.0 op_sel_hi:[1,0]
	v_pk_add_f32 v[222:223], v[222:223], 1.0 op_sel_hi:[1,0]
	v_rcp_f32_e32 v220, v220
	v_rcp_f32_e32 v221, v221
	v_rcp_f32_e32 v222, v222
	v_rcp_f32_e32 v223, v223
	v_pk_mul_f32 v[216:217], v[216:217], v[220:221]
	v_pk_mul_f32 v[218:219], v[218:219], v[222:223]
	v_pk_mul_f32 v[220:221], v[88:89], v[136:137] op_sel_hi:[1,0]
	v_pk_mul_f32 v[222:223], v[90:91], v[136:137] op_sel_hi:[1,0]
	v_pk_mul_f32 v[216:217], v[220:221], v[216:217]
	v_pk_mul_f32 v[218:219], v[222:223], v[218:219]
	v_cvt_pk_bf16_f32 v134, v216, v217
	v_cvt_pk_bf16_f32 v135, v218, v219
	v_mov_b32_e32 v248, v134
	v_mov_b32_e32 v249, v135
	v_mul_f32_e32 v134, v84, v136
	v_mul_f32_e32 v135, 0xbfb8aa3b, v134
	v_exp_f32_e32 v135, v135
	s_nop 0
	v_add_f32_e32 v135, 1.0, v135
	v_rcp_f32_e32 v135, v135
	s_nop 0
	v_mul_f32_e32 v134, v134, v135
	v_mul_f32_e32 v135, v80, v136
	v_mul_f32_e32 v134, v135, v134
	v_mul_f32_e32 v135, v85, v136
	v_mul_f32_e32 v137, 0xbfb8aa3b, v135
	v_exp_f32_e32 v137, v137
	s_nop 0
	v_add_f32_e32 v137, 1.0, v137
	v_rcp_f32_e32 v137, v137
	s_nop 0
	v_mul_f32_e32 v135, v135, v137
	v_mul_f32_e32 v137, v81, v136
	v_mul_f32_e32 v135, v137, v135
	v_mul_f32_e32 v137, v86, v136
	v_mul_f32_e32 v138, 0xbfb8aa3b, v137
	v_exp_f32_e32 v138, v138
	v_cvt_pk_bf16_f32 v134, v134, v135
	s_nop 0
	v_add_f32_e32 v138, 1.0, v138
	v_rcp_f32_e32 v138, v138
	s_nop 0
	v_mul_f32_e32 v137, v137, v138
	v_mul_f32_e32 v138, v82, v136
	v_mul_f32_e32 v137, v138, v137
	v_mul_f32_e32 v138, v87, v136
	v_mul_f32_e32 v139, 0xbfb8aa3b, v138
	v_exp_f32_e32 v139, v139
	v_mul_f32_e32 v136, v83, v136
	v_add_f32_e32 v139, 1.0, v139
	v_rcp_f32_e32 v139, v139
	s_nop 0
	v_mul_f32_e32 v138, v138, v139
	v_mul_f32_e32 v136, v136, v138
	v_cvt_pk_bf16_f32 v135, v137, v136
	v_mov_b32_e32 v250, v134
	v_mov_b32_e32 v251, v135
	s_nop 1
	v_permlane16_swap_b32 v248, v250
	v_permlane16_swap_b32 v249, v251
	flat_store_dwordx4 v[132:133], v[248:251]
	ds_read_b32 v136, v130 offset:192
	v_or_b32_e32 v132, 48, v131
	v_mad_i64_i32 v[132:133], s[2:3], v132, s33, v[128:129]
	s_waitcnt lgkmcnt(0)
	s_nop 0
	v_pk_mul_f32 v[216:217], v[76:77], v[136:137] op_sel_hi:[1,0]
	v_pk_mul_f32 v[218:219], v[78:79], v[136:137] op_sel_hi:[1,0]
	v_pk_mul_f32 v[220:221], v[216:217], s[98:99] op_sel_hi:[1,0]
	v_pk_mul_f32 v[222:223], v[218:219], s[98:99] op_sel_hi:[1,0]
	v_exp_f32_e32 v220, v220
	v_exp_f32_e32 v221, v221
	v_exp_f32_e32 v222, v222
	v_exp_f32_e32 v223, v223
	v_pk_add_f32 v[220:221], v[220:221], 1.0 op_sel_hi:[1,0]
	v_pk_add_f32 v[222:223], v[222:223], 1.0 op_sel_hi:[1,0]
	v_rcp_f32_e32 v220, v220
	v_rcp_f32_e32 v221, v221
	v_rcp_f32_e32 v222, v222
	v_rcp_f32_e32 v223, v223
	v_pk_mul_f32 v[216:217], v[216:217], v[220:221]
	v_pk_mul_f32 v[218:219], v[218:219], v[222:223]
	v_pk_mul_f32 v[220:221], v[72:73], v[136:137] op_sel_hi:[1,0]
	v_pk_mul_f32 v[222:223], v[74:75], v[136:137] op_sel_hi:[1,0]
	v_pk_mul_f32 v[216:217], v[220:221], v[216:217]
	v_pk_mul_f32 v[218:219], v[222:223], v[218:219]
	v_cvt_pk_bf16_f32 v134, v216, v217
	v_cvt_pk_bf16_f32 v135, v218, v219
	v_mov_b32_e32 v248, v134
	v_mov_b32_e32 v249, v135
	v_mul_f32_e32 v134, v68, v136
	v_mul_f32_e32 v135, 0xbfb8aa3b, v134
	v_exp_f32_e32 v135, v135
	s_nop 0
	v_add_f32_e32 v135, 1.0, v135
	v_rcp_f32_e32 v135, v135
	s_nop 0
	v_mul_f32_e32 v134, v134, v135
	v_mul_f32_e32 v135, v64, v136
	v_mul_f32_e32 v134, v135, v134
	v_mul_f32_e32 v135, v69, v136
	v_mul_f32_e32 v137, 0xbfb8aa3b, v135
	v_exp_f32_e32 v137, v137
	s_nop 0
	v_add_f32_e32 v137, 1.0, v137
	v_rcp_f32_e32 v137, v137
	s_nop 0
	v_mul_f32_e32 v135, v135, v137
	v_mul_f32_e32 v137, v65, v136
	v_mul_f32_e32 v135, v137, v135
	v_mul_f32_e32 v137, v70, v136
	v_mul_f32_e32 v138, 0xbfb8aa3b, v137
	v_exp_f32_e32 v138, v138
	v_cvt_pk_bf16_f32 v134, v134, v135
	s_nop 0
	v_add_f32_e32 v138, 1.0, v138
	v_rcp_f32_e32 v138, v138
	s_nop 0
	v_mul_f32_e32 v137, v137, v138
	v_mul_f32_e32 v138, v66, v136
	v_mul_f32_e32 v137, v138, v137
	v_mul_f32_e32 v138, v71, v136
	v_mul_f32_e32 v139, 0xbfb8aa3b, v138
	v_exp_f32_e32 v139, v139
	v_mul_f32_e32 v136, v67, v136
	v_add_f32_e32 v139, 1.0, v139
	v_rcp_f32_e32 v139, v139
	s_nop 0
	v_mul_f32_e32 v138, v138, v139
	v_mul_f32_e32 v136, v136, v138
	v_cvt_pk_bf16_f32 v135, v137, v136
	v_mov_b32_e32 v250, v134
	v_mov_b32_e32 v251, v135
	s_nop 1
	v_permlane16_swap_b32 v248, v250
	v_permlane16_swap_b32 v249, v251
	flat_store_dwordx4 v[132:133], v[248:251]
	ds_read_b32 v136, v130 offset:256
	v_or_b32_e32 v132, 64, v131
	v_mad_i64_i32 v[132:133], s[2:3], v132, s33, v[128:129]
	s_waitcnt lgkmcnt(0)
	s_nop 0
	v_pk_mul_f32 v[216:217], v[60:61], v[136:137] op_sel_hi:[1,0]
	v_pk_mul_f32 v[218:219], v[62:63], v[136:137] op_sel_hi:[1,0]
	v_pk_mul_f32 v[220:221], v[216:217], s[98:99] op_sel_hi:[1,0]
	v_pk_mul_f32 v[222:223], v[218:219], s[98:99] op_sel_hi:[1,0]
	v_exp_f32_e32 v220, v220
	v_exp_f32_e32 v221, v221
	v_exp_f32_e32 v222, v222
	v_exp_f32_e32 v223, v223
	v_pk_add_f32 v[220:221], v[220:221], 1.0 op_sel_hi:[1,0]
	v_pk_add_f32 v[222:223], v[222:223], 1.0 op_sel_hi:[1,0]
	v_rcp_f32_e32 v220, v220
	v_rcp_f32_e32 v221, v221
	v_rcp_f32_e32 v222, v222
	v_rcp_f32_e32 v223, v223
	v_pk_mul_f32 v[216:217], v[216:217], v[220:221]
	v_pk_mul_f32 v[218:219], v[218:219], v[222:223]
	v_pk_mul_f32 v[220:221], v[56:57], v[136:137] op_sel_hi:[1,0]
	v_pk_mul_f32 v[222:223], v[58:59], v[136:137] op_sel_hi:[1,0]
	v_pk_mul_f32 v[216:217], v[220:221], v[216:217]
	v_pk_mul_f32 v[218:219], v[222:223], v[218:219]
	v_cvt_pk_bf16_f32 v134, v216, v217
	v_cvt_pk_bf16_f32 v135, v218, v219
	v_mov_b32_e32 v248, v134
	v_mov_b32_e32 v249, v135
	v_mul_f32_e32 v134, v52, v136
	v_mul_f32_e32 v135, 0xbfb8aa3b, v134
	v_exp_f32_e32 v135, v135
	s_nop 0
	v_add_f32_e32 v135, 1.0, v135
	v_rcp_f32_e32 v135, v135
	s_nop 0
	v_mul_f32_e32 v134, v134, v135
	v_mul_f32_e32 v135, v48, v136
	v_mul_f32_e32 v134, v135, v134
	v_mul_f32_e32 v135, v53, v136
	v_mul_f32_e32 v137, 0xbfb8aa3b, v135
	v_exp_f32_e32 v137, v137
	s_nop 0
	v_add_f32_e32 v137, 1.0, v137
	v_rcp_f32_e32 v137, v137
	s_nop 0
	v_mul_f32_e32 v135, v135, v137
	v_mul_f32_e32 v137, v49, v136
	v_mul_f32_e32 v135, v137, v135
	v_mul_f32_e32 v137, v54, v136
	v_mul_f32_e32 v138, 0xbfb8aa3b, v137
	v_exp_f32_e32 v138, v138
	v_cvt_pk_bf16_f32 v134, v134, v135
	s_nop 0
	v_add_f32_e32 v138, 1.0, v138
	v_rcp_f32_e32 v138, v138
	s_nop 0
	v_mul_f32_e32 v137, v137, v138
	v_mul_f32_e32 v138, v50, v136
	v_mul_f32_e32 v137, v138, v137
	v_mul_f32_e32 v138, v55, v136
	v_mul_f32_e32 v139, 0xbfb8aa3b, v138
	v_exp_f32_e32 v139, v139
	v_mul_f32_e32 v136, v51, v136
	v_add_f32_e32 v139, 1.0, v139
	v_rcp_f32_e32 v139, v139
	s_nop 0
	v_mul_f32_e32 v138, v138, v139
	v_mul_f32_e32 v136, v136, v138
	v_cvt_pk_bf16_f32 v135, v137, v136
	v_mov_b32_e32 v250, v134
	v_mov_b32_e32 v251, v135
	s_nop 1
	v_permlane16_swap_b32 v248, v250
	v_permlane16_swap_b32 v249, v251
	flat_store_dwordx4 v[132:133], v[248:251]
	ds_read_b32 v136, v130 offset:320
	v_or_b32_e32 v132, 0x50, v131
	v_mad_i64_i32 v[132:133], s[2:3], v132, s33, v[128:129]
	s_waitcnt lgkmcnt(0)
	s_nop 0
	v_pk_mul_f32 v[216:217], v[44:45], v[136:137] op_sel_hi:[1,0]
	v_pk_mul_f32 v[218:219], v[46:47], v[136:137] op_sel_hi:[1,0]
	v_pk_mul_f32 v[220:221], v[216:217], s[98:99] op_sel_hi:[1,0]
	v_pk_mul_f32 v[222:223], v[218:219], s[98:99] op_sel_hi:[1,0]
	v_exp_f32_e32 v220, v220
	v_exp_f32_e32 v221, v221
	v_exp_f32_e32 v222, v222
	v_exp_f32_e32 v223, v223
	v_pk_add_f32 v[220:221], v[220:221], 1.0 op_sel_hi:[1,0]
	v_pk_add_f32 v[222:223], v[222:223], 1.0 op_sel_hi:[1,0]
	v_rcp_f32_e32 v220, v220
	v_rcp_f32_e32 v221, v221
	v_rcp_f32_e32 v222, v222
	v_rcp_f32_e32 v223, v223
	v_pk_mul_f32 v[216:217], v[216:217], v[220:221]
	v_pk_mul_f32 v[218:219], v[218:219], v[222:223]
	v_pk_mul_f32 v[220:221], v[40:41], v[136:137] op_sel_hi:[1,0]
	v_pk_mul_f32 v[222:223], v[42:43], v[136:137] op_sel_hi:[1,0]
	v_pk_mul_f32 v[216:217], v[220:221], v[216:217]
	v_pk_mul_f32 v[218:219], v[222:223], v[218:219]
	v_cvt_pk_bf16_f32 v134, v216, v217
	v_cvt_pk_bf16_f32 v135, v218, v219
	v_mov_b32_e32 v248, v134
	v_mov_b32_e32 v249, v135
	v_mul_f32_e32 v134, v36, v136
	v_mul_f32_e32 v135, 0xbfb8aa3b, v134
	v_exp_f32_e32 v135, v135
	s_nop 0
	v_add_f32_e32 v135, 1.0, v135
	v_rcp_f32_e32 v135, v135
	s_nop 0
	v_mul_f32_e32 v134, v134, v135
	v_mul_f32_e32 v135, v32, v136
	v_mul_f32_e32 v134, v135, v134
	v_mul_f32_e32 v135, v37, v136
	v_mul_f32_e32 v137, 0xbfb8aa3b, v135
	v_exp_f32_e32 v137, v137
	s_nop 0
	v_add_f32_e32 v137, 1.0, v137
	v_rcp_f32_e32 v137, v137
	s_nop 0
	v_mul_f32_e32 v135, v135, v137
	v_mul_f32_e32 v137, v33, v136
	v_mul_f32_e32 v135, v137, v135
	v_mul_f32_e32 v137, v38, v136
	v_mul_f32_e32 v138, 0xbfb8aa3b, v137
	v_exp_f32_e32 v138, v138
	v_cvt_pk_bf16_f32 v134, v134, v135
	s_nop 0
	v_add_f32_e32 v138, 1.0, v138
	v_rcp_f32_e32 v138, v138
	s_nop 0
	v_mul_f32_e32 v137, v137, v138
	v_mul_f32_e32 v138, v34, v136
	v_mul_f32_e32 v137, v138, v137
	v_mul_f32_e32 v138, v39, v136
	v_mul_f32_e32 v139, 0xbfb8aa3b, v138
	v_exp_f32_e32 v139, v139
	v_mul_f32_e32 v136, v35, v136
	v_add_f32_e32 v139, 1.0, v139
	v_rcp_f32_e32 v139, v139
	s_nop 0
	v_mul_f32_e32 v138, v138, v139
	v_mul_f32_e32 v136, v136, v138
	v_cvt_pk_bf16_f32 v135, v137, v136
	v_mov_b32_e32 v250, v134
	v_mov_b32_e32 v251, v135
	s_nop 1
	v_permlane16_swap_b32 v248, v250
	v_permlane16_swap_b32 v249, v251
	flat_store_dwordx4 v[132:133], v[248:251]
	ds_read_b32 v136, v130 offset:384
	v_or_b32_e32 v132, 0x60, v131
	v_mad_i64_i32 v[132:133], s[2:3], v132, s33, v[128:129]
	v_or_b32_e32 v131, 0x70, v131
	s_waitcnt lgkmcnt(0)
	v_mad_i64_i32 v[128:129], s[2:3], v131, s33, v[128:129]
	s_nop 0
	v_pk_mul_f32 v[216:217], v[28:29], v[136:137] op_sel_hi:[1,0]
	v_pk_mul_f32 v[218:219], v[30:31], v[136:137] op_sel_hi:[1,0]
	v_pk_mul_f32 v[220:221], v[216:217], s[98:99] op_sel_hi:[1,0]
	v_pk_mul_f32 v[222:223], v[218:219], s[98:99] op_sel_hi:[1,0]
	v_exp_f32_e32 v220, v220
	v_exp_f32_e32 v221, v221
	v_exp_f32_e32 v222, v222
	v_exp_f32_e32 v223, v223
	v_pk_add_f32 v[220:221], v[220:221], 1.0 op_sel_hi:[1,0]
	v_pk_add_f32 v[222:223], v[222:223], 1.0 op_sel_hi:[1,0]
	v_rcp_f32_e32 v220, v220
	v_rcp_f32_e32 v221, v221
	v_rcp_f32_e32 v222, v222
	v_rcp_f32_e32 v223, v223
	v_pk_mul_f32 v[216:217], v[216:217], v[220:221]
	v_pk_mul_f32 v[218:219], v[218:219], v[222:223]
	v_pk_mul_f32 v[220:221], v[24:25], v[136:137] op_sel_hi:[1,0]
	v_pk_mul_f32 v[222:223], v[26:27], v[136:137] op_sel_hi:[1,0]
	v_pk_mul_f32 v[216:217], v[220:221], v[216:217]
	v_pk_mul_f32 v[218:219], v[222:223], v[218:219]
	v_cvt_pk_bf16_f32 v134, v216, v217
	v_cvt_pk_bf16_f32 v135, v218, v219
	v_mov_b32_e32 v248, v134
	v_mov_b32_e32 v249, v135
	v_mul_f32_e32 v134, v20, v136
	v_mul_f32_e32 v135, 0xbfb8aa3b, v134
	v_exp_f32_e32 v135, v135
	s_nop 0
	v_add_f32_e32 v135, 1.0, v135
	v_rcp_f32_e32 v135, v135
	s_nop 0
	v_mul_f32_e32 v134, v134, v135
	v_mul_f32_e32 v135, v16, v136
	v_mul_f32_e32 v134, v135, v134
	v_mul_f32_e32 v135, v21, v136
	v_mul_f32_e32 v137, 0xbfb8aa3b, v135
	v_exp_f32_e32 v137, v137
	s_nop 0
	v_add_f32_e32 v137, 1.0, v137
	v_rcp_f32_e32 v137, v137
	s_nop 0
	v_mul_f32_e32 v135, v135, v137
	v_mul_f32_e32 v137, v17, v136
	v_mul_f32_e32 v135, v137, v135
	v_mul_f32_e32 v137, v22, v136
	v_mul_f32_e32 v138, 0xbfb8aa3b, v137
	v_exp_f32_e32 v138, v138
	v_cvt_pk_bf16_f32 v134, v134, v135
	s_nop 0
	v_add_f32_e32 v138, 1.0, v138
	v_rcp_f32_e32 v138, v138
	s_nop 0
	v_mul_f32_e32 v137, v137, v138
	v_mul_f32_e32 v138, v18, v136
	v_mul_f32_e32 v137, v138, v137
	v_mul_f32_e32 v138, v23, v136
	v_mul_f32_e32 v139, 0xbfb8aa3b, v138
	v_exp_f32_e32 v139, v139
	v_mul_f32_e32 v136, v19, v136
	v_add_f32_e32 v139, 1.0, v139
	v_rcp_f32_e32 v139, v139
	s_nop 0
	v_mul_f32_e32 v138, v138, v139
	v_mul_f32_e32 v136, v136, v138
	v_cvt_pk_bf16_f32 v135, v137, v136
	v_mov_b32_e32 v250, v134
	v_mov_b32_e32 v251, v135
	s_nop 1
	v_permlane16_swap_b32 v248, v250
	v_permlane16_swap_b32 v249, v251
	flat_store_dwordx4 v[132:133], v[248:251]
	ds_read_b32 v132, v130 offset:448
	s_waitcnt lgkmcnt(0)
	s_nop 0
	v_pk_mul_f32 v[216:217], v[12:13], v[132:133] op_sel_hi:[1,0]
	v_pk_mul_f32 v[218:219], v[14:15], v[132:133] op_sel_hi:[1,0]
	v_pk_mul_f32 v[220:221], v[216:217], s[98:99] op_sel_hi:[1,0]
	v_pk_mul_f32 v[222:223], v[218:219], s[98:99] op_sel_hi:[1,0]
	v_exp_f32_e32 v220, v220
	v_exp_f32_e32 v221, v221
	v_exp_f32_e32 v222, v222
	v_exp_f32_e32 v223, v223
	v_pk_add_f32 v[220:221], v[220:221], 1.0 op_sel_hi:[1,0]
	v_pk_add_f32 v[222:223], v[222:223], 1.0 op_sel_hi:[1,0]
	v_rcp_f32_e32 v220, v220
	v_rcp_f32_e32 v221, v221
	v_rcp_f32_e32 v222, v222
	v_rcp_f32_e32 v223, v223
	v_pk_mul_f32 v[216:217], v[216:217], v[220:221]
	v_pk_mul_f32 v[218:219], v[218:219], v[222:223]
	v_pk_mul_f32 v[220:221], v[8:9], v[132:133] op_sel_hi:[1,0]
	v_pk_mul_f32 v[222:223], v[10:11], v[132:133] op_sel_hi:[1,0]
	v_pk_mul_f32 v[216:217], v[220:221], v[216:217]
	v_pk_mul_f32 v[218:219], v[222:223], v[218:219]
	v_cvt_pk_bf16_f32 v130, v216, v217
	v_cvt_pk_bf16_f32 v131, v218, v219
	v_mov_b32_e32 v248, v130
	v_mov_b32_e32 v249, v131
	v_mul_f32_e32 v130, v4, v132
	v_mul_f32_e32 v131, 0xbfb8aa3b, v130
	v_exp_f32_e32 v131, v131
	s_nop 0
	v_add_f32_e32 v131, 1.0, v131
	v_rcp_f32_e32 v131, v131
	s_nop 0
	v_mul_f32_e32 v130, v130, v131
	v_mul_f32_e32 v131, v0, v132
	v_mul_f32_e32 v130, v131, v130
	v_mul_f32_e32 v131, v5, v132
	v_mul_f32_e32 v133, 0xbfb8aa3b, v131
	v_exp_f32_e32 v133, v133
	s_nop 0
	v_add_f32_e32 v133, 1.0, v133
	v_rcp_f32_e32 v133, v133
	s_nop 0
	v_mul_f32_e32 v131, v131, v133
	v_mul_f32_e32 v133, v1, v132
	v_mul_f32_e32 v131, v133, v131
	v_mul_f32_e32 v133, v6, v132
	v_mul_f32_e32 v134, 0xbfb8aa3b, v133
	v_exp_f32_e32 v134, v134
	v_cvt_pk_bf16_f32 v130, v130, v131
	s_nop 0
	v_add_f32_e32 v134, 1.0, v134
	v_rcp_f32_e32 v134, v134
	s_nop 0
	v_mul_f32_e32 v133, v133, v134
	v_mul_f32_e32 v134, v2, v132
	v_mul_f32_e32 v133, v134, v133
	v_mul_f32_e32 v134, v7, v132
	v_mul_f32_e32 v135, 0xbfb8aa3b, v134
	v_exp_f32_e32 v135, v135
	v_mul_f32_e32 v132, v3, v132
	v_add_f32_e32 v135, 1.0, v135
	v_rcp_f32_e32 v135, v135
	s_nop 0
	v_mul_f32_e32 v134, v134, v135
	v_mul_f32_e32 v132, v132, v134
	v_cvt_pk_bf16_f32 v131, v133, v132
	v_mov_b32_e32 v250, v130
	v_mov_b32_e32 v251, v131
	s_nop 1
	v_permlane16_swap_b32 v248, v250
	v_permlane16_swap_b32 v249, v251
	flat_store_dwordx4 v[128:129], v[248:251]
	s_cbranch_execnz .LBB0_653
	s_branch .LBB0_676
